# speedup vs baseline: 1.0006x; 1.0006x over previous
; #define A64_GLOAD(t) do { A64_IDX(); const char* Kt = (const char*)(Kg + (size_t)(t) * 64 * ldk); const char* Vt = (const char*)(Vg + (size_t)(t) * 64 * ldv); \
;         kreg0 = *(const u32x4*)(Kt + (unsigned)(kk0 * ldk + kc0 * 8) * 2u); if (k2) kreg1 = *(const u32x4*)(Kt + (unsigned)(kk1 * ldk + kc1 * 8) * 2u); vreg = *(const u32x4*)(Vt + (unsigned)(vk * ldv + vc * 8) * 2u); } while (0)
; #define A64_LWRITE(bo) do { A64_IDX(); *(LAS u32x4*)(lds + (bo) + kk0 * KP + kc0 * 16) = kreg0; if (k2) *(LAS u32x4*)(lds + (bo) + kk1 * KP + kc1 * 16) = kreg1; \
;         *(LAS u32x4*)(lds + (bo) + KBYTES + (vc >> 2) * 4096 + vk * 64 + (vc & 3) * 16) = vreg; } while (0)
; #define A64_KREAD(bo, half) do { _Pragma("unroll") for (int ds = 0; ds < NDS; ++ds) kf[ds] = *(const LAS bf16x8*)(lds + (bo) + kfr + (half) * 32 * KP + ds * 32); } while (0)
; template <int DQK>
; __device__ __forceinline__ void attn_unit64p(LAS char* lds, const bf16x8 (&qa)[DQK / 16], const bf16x8 (&qb)[DQK / 16],
;                                              const bf16_t* Kg, int ldk, const bf16_t* Vg, int ldv, int nt, bf16_t* Obase, int ldo, int ogb_off) {
;     ...
;     f32x16 oa0, oa1, ob0, ob1, sa, sb;
; #pragma unroll
;     for (int i = 0; i < 16; ++i) { oa0[i] = 0.f; oa1[i] = 0.f; ob0[i] = 0.f; ob1[i] = 0.f; sa[i] = 0.f; sb[i] = NEG_BIG; }
;     float la0 = 0.f, la1 = 0.f, lb0 = 0.f, lb1 = 0.f;
;     bf16x8 kf[NDS], vf[4], pa[2], pb[2];
; #pragma unroll
;     for (int i = 0; i < 4; ++i) vf[i] = (bf16x8){0, 0, 0, 0, 0, 0, 0, 0};
;     u32x4 kreg0, kreg1 = (u32x4){0u, 0u, 0u, 0u}, vreg;
;     ...
;     A64_GLOAD(0); A64_LWRITE(0);
;     __syncthreads();
;     if (nt > 1) A64_GLOAD(1);
;     A64_KREAD(0, 0);
; #pragma nounroll
;     for (int j = 0; j < 2 * nt; ++j) {
.Lp11_g1_pro:
	s_mov_b32 s24, 0x2000
	s_mov_b32 s25, 0
	v_lshl_add_u64 v[180:181], v[168:169], 0, s[24:25]
	global_load_dwordx4 v[104:107], v[180:181], off
	v_mov_b32_e32 v64, 0xf149f2ca
	v_mov_b32_e32 v65, v64
	v_mov_b32_e32 v66, v64
	v_mov_b32_e32 v67, v64
	v_mov_b32_e32 v68, v64
	v_mov_b32_e32 v69, v64
	v_mov_b32_e32 v70, v64
	v_mov_b32_e32 v71, v64
	v_mov_b32_e32 v72, v64
	v_mov_b32_e32 v73, v64
	v_mov_b32_e32 v74, v64
	v_mov_b32_e32 v75, v64
	v_mov_b32_e32 v76, v64
	v_mov_b32_e32 v77, v64
	v_mov_b32_e32 v78, v64
	v_mov_b32_e32 v79, v64
	v_mov_b32_e32 v214, 0
	v_mov_b32_e32 v215, 0
	v_mov_b32_e32 v216, 0
	v_mov_b32_e32 v217, 0
	v_mov_b32_e32 v218, 0
	v_mov_b32_e32 v219, 0
	v_mov_b32_e32 v220, 0
	v_mov_b32_e32 v221, 0
	v_mov_b32_e32 v248, 0
	v_mov_b32_e32 v249, 0
	v_mov_b32_e32 v250, 0
	v_mov_b32_e32 v251, 0
	v_mov_b32_e32 v252, 0
	v_mov_b32_e32 v253, 0
	v_mov_b32_e32 v254, 0
	v_mov_b32_e32 v255, 0
	s_cmp_eq_u64 s[0:1], 0
	s_cbranch_scc1 .Lp11_noprio
	s_setprio 3
